# second half-step QK: K fragments in three register sets (third = v[100:103],v[136:139], free there), each pair read two pairs early
# baseline (speedup 1.0000x reference)
; __device__ __forceinline__ void partialSM(f32x16& p0, f32x16& p1, float& m_reg, float& mn, float& alpha, bool rs) {
;     ...
;     const float mnL = rs ? -mn * C2 : -__builtin_inff();
;     for (int r = 0; r < 16; ++r) p0[r] = fmaf(p0[r], C2, mnL); for (int r = 0; r < 16; ++r) p1[r] = fmaf(p1[r], C2, mnL);
;     for (int r = 0; r < 16; ++r) p0[r] = __builtin_amdgcn_exp2f(p0[r]);
; }
; __device__ __forceinline__ void finishSM(f32x16& p0, f32x16& p1, float alpha, float& l_reg, bf16x8& pa0, bf16x8& pa1, bf16x8& pa2, bf16x8& pa3) {
;     for (int r = 0; r < 16; ++r) p1[r] = __builtin_amdgcn_exp2f(p1[r]);
;     float ps = 0; for (int r = 0; r < 16; ++r) ps += p0[r]; for (int r = 0; r < 16; ++r) ps += p1[r];
;     { auto rr = __builtin_amdgcn_permlane32_swap(__float_as_uint(ps), __float_as_uint(ps), false, false);
;       ps = __uint_as_float(rr[0]) + __uint_as_float(rr[1]); }
;     l_reg = l_reg * alpha + ps;
; template <int KB>
; __device__ __forceinline__ void qkt(f32x16& p0, f32x16& p1, const char* K_lds, int r32, int hi, const bf16x8* qr) {
;     p0 = f32x16{}; p1 = f32x16{};
;     const char* kb[4];
; #pragma unroll
;     for (int dd = 0; dd < 4; ++dd) kb[dd] = K_lds + KB * SHM_K + KSWZ(r32, (dd * 16 + hi * 8) * 2);
; #pragma unroll
;     for (int d0 = 0; d0 < 8; ++d0) { const char* a = kb[d0 & 3] + (d0 >> 2) * 128;
;         bf16x8 b0 = *reinterpret_cast<const bf16x8*>(a);
;         bf16x8 b1 = *reinterpret_cast<const bf16x8*>(a + 32 * 256);
;         p0 = __builtin_amdgcn_mfma_f32_32x32x16_bf16(b0, qr[d0], p0, 0, 0, 0);
;         p1 = __builtin_amdgcn_mfma_f32_32x32x16_bf16(b1, qr[d0], p1, 0, 0, 0); }
.LBB0_95:
	v_cndmask_b32_e64 v179, v148, v198, s[42:43]
	v_mul_f32_e32 v148, 0xbe0293ee, v179
	v_cndmask_b32_e64 v180, v220, v148, s[40:41]
	v_fmamk_f32 v82, v82, 0x3e0293ee, v180
	v_fmamk_f32 v83, v83, 0x3e0293ee, v180
	v_fmamk_f32 v84, v84, 0x3e0293ee, v180
	v_fmamk_f32 v85, v85, 0x3e0293ee, v180
	v_fmamk_f32 v86, v86, 0x3e0293ee, v180
	v_fmamk_f32 v87, v87, 0x3e0293ee, v180
	v_fmamk_f32 v88, v88, 0x3e0293ee, v180
	v_fmamk_f32 v89, v89, 0x3e0293ee, v180
	v_fmamk_f32 v90, v90, 0x3e0293ee, v180
	v_fmamk_f32 v91, v91, 0x3e0293ee, v180
	v_fmamk_f32 v92, v92, 0x3e0293ee, v180
	v_fmamk_f32 v93, v93, 0x3e0293ee, v180
	v_fmamk_f32 v94, v94, 0x3e0293ee, v180
	v_fmamk_f32 v95, v95, 0x3e0293ee, v180
	v_fmamk_f32 v96, v96, 0x3e0293ee, v180
	v_fmamk_f32 v97, v97, 0x3e0293ee, v180
	v_exp_f32_e32 v148, v82
	v_exp_f32_e32 v163, v83
	v_exp_f32_e32 v149, v84
	v_exp_f32_e32 v162, v85
	v_exp_f32_e32 v150, v86
	v_exp_f32_e32 v161, v87
	v_exp_f32_e32 v151, v88
	v_exp_f32_e32 v160, v89
	v_exp_f32_e32 v152, v90
	v_exp_f32_e32 v159, v91
	v_exp_f32_e32 v153, v92
	v_exp_f32_e32 v158, v93
	v_exp_f32_e32 v154, v94
	v_exp_f32_e32 v157, v95
	v_exp_f32_e32 v155, v96
	v_exp_f32_e32 v156, v97
	v_fmamk_f32 v203, v73, 0x3e0293ee, v180
	v_fmamk_f32 v204, v74, 0x3e0293ee, v180
	v_fmamk_f32 v208, v66, 0x3e0293ee, v180
	v_fmamk_f32 v209, v67, 0x3e0293ee, v180
	v_fmamk_f32 v223, v68, 0x3e0293ee, v180
	v_fmamk_f32 v224, v69, 0x3e0293ee, v180
	v_fmamk_f32 v225, v70, 0x3e0293ee, v180
	v_fmamk_f32 v198, v71, 0x3e0293ee, v180
	v_fmamk_f32 v201, v72, 0x3e0293ee, v180
	v_fmamk_f32 v205, v75, 0x3e0293ee, v180
	v_fmamk_f32 v206, v76, 0x3e0293ee, v180
	v_fmamk_f32 v207, v77, 0x3e0293ee, v180
	v_fmamk_f32 v181, v78, 0x3e0293ee, v180
	v_fmamk_f32 v226, v79, 0x3e0293ee, v180
	v_fmamk_f32 v227, v80, 0x3e0293ee, v180
	v_fmac_f32_e32 v180, 0x3e0293ee, v81
	s_waitcnt lgkmcnt(0)
	ds_read_b128 v[66:69], v169 offset:32768
	ds_read_b128 v[70:73], v169 offset:40960
	ds_read_b128 v[172:175], v193 offset:32768
	ds_read_b128 v[228:231], v193 offset:40960
	ds_read_b128 v[234:237], v194 offset:32768
	ds_read_b128 v[238:241], v194 offset:40960
	ds_read_b128 v[100:103], v195 offset:32768
	ds_read_b128 v[136:139], v195 offset:40960
	v_exp_f32_e32 v198, v198
	v_exp_f32_e32 v201, v201
	v_exp_f32_e32 v214, v204
	v_exp_f32_e32 v205, v205
	v_exp_f32_e32 v206, v206
	v_exp_f32_e32 v207, v207
	v_exp_f32_e32 v181, v181
	v_exp_f32_e32 v215, v226
	v_exp_f32_e32 v216, v227
	v_exp_f32_e32 v180, v180
	v_exp_f32_e32 v218, v209
	v_exp_f32_e32 v209, v203
	v_add_f32_e32 v203, 0, v148
	v_add_f32_e32 v203, v163, v203
	v_add_f32_e32 v203, v149, v203
	v_add_f32_e32 v203, v162, v203
	v_add_f32_e32 v203, v150, v203
	v_add_f32_e32 v203, v161, v203
	v_add_f32_e32 v203, v151, v203
	v_add_f32_e32 v203, v160, v203
	s_waitcnt lgkmcnt(7)
	v_mfma_f32_32x32x16_bf16 v[82:97], v[66:69], v[132:135], 0
	v_add_f32_e32 v203, v152, v203
	v_add_f32_e32 v203, v159, v203
	v_add_f32_e32 v203, v153, v203
	v_add_f32_e32 v203, v158, v203
	s_waitcnt lgkmcnt(6)
	v_mfma_f32_32x32x16_bf16 v[66:81], v[70:73], v[132:135], 0
	v_exp_f32_e32 v217, v208
	v_add_f32_e32 v203, v154, v203
	v_add_f32_e32 v203, v157, v203
	v_exp_f32_e32 v219, v223
	s_waitcnt lgkmcnt(5)
	v_mfma_f32_32x32x16_bf16 v[82:97], v[172:175], v[128:131], v[82:97]
	v_add_f32_e32 v203, v155, v203
	v_exp_f32_e32 v222, v224
	v_add_f32_e32 v203, v156, v203
	v_exp_f32_e32 v208, v225
	s_waitcnt lgkmcnt(4)
	v_mfma_f32_32x32x16_bf16 v[66:81], v[228:231], v[128:131], v[66:81]
	v_add_f32_e32 v203, v217, v203
	v_add_f32_e32 v203, v218, v203
	v_add_f32_e32 v203, v219, v203
	v_add_f32_e32 v203, v222, v203
	ds_read_b128 v[172:175], v169 offset:32896
	ds_read_b128 v[228:231], v169 offset:41088
	s_waitcnt lgkmcnt(5)
; __device__ __forceinline__ void finishSM(f32x16& p0, f32x16& p1, float alpha, float& l_reg, bf16x8& pa0, bf16x8& pa1, bf16x8& pa2, bf16x8& pa3) {
;     ...
;     PK4(p0, 0, pa0); PK4(p0, 8, pa1); PK4(p1, 0, pa2); PK4(p1, 8, pa3);
; template <int KB>
; __device__ __forceinline__ void qkt(f32x16& p0, f32x16& p1, const char* K_lds, int r32, int hi, const bf16x8* qr) {
;     p0 = f32x16{}; p1 = f32x16{};
;     const char* kb[4];
; #pragma unroll
;     for (int dd = 0; dd < 4; ++dd) kb[dd] = K_lds + KB * SHM_K + KSWZ(r32, (dd * 16 + hi * 8) * 2);
; #pragma unroll
;     for (int d0 = 0; d0 < 8; ++d0) { const char* a = kb[d0 & 3] + (d0 >> 2) * 128;
;         bf16x8 b0 = *reinterpret_cast<const bf16x8*>(a);
;         bf16x8 b1 = *reinterpret_cast<const bf16x8*>(a + 32 * 256);
;         p0 = __builtin_amdgcn_mfma_f32_32x32x16_bf16(b0, qr[d0], p0, 0, 0, 0);
;         p1 = __builtin_amdgcn_mfma_f32_32x32x16_bf16(b1, qr[d0], p1, 0, 0, 0); }
; }
	v_mfma_f32_32x32x16_bf16 v[82:97], v[234:237], v[124:127], v[82:97]
	v_add_f32_e32 v203, v208, v203
	v_add_f32_e32 v203, v198, v203
	v_add_f32_e32 v203, v201, v203
	v_add_f32_e32 v203, v209, v203
	s_waitcnt lgkmcnt(4)
	v_mfma_f32_32x32x16_bf16 v[66:81], v[238:241], v[124:127], v[66:81]
	v_add_f32_e32 v203, v214, v203
	v_add_f32_e32 v203, v205, v203
	v_add_f32_e32 v203, v206, v203
	v_add_f32_e32 v203, v207, v203
	ds_read_b128 v[234:237], v193 offset:32896
	ds_read_b128 v[238:241], v193 offset:41088
	s_waitcnt lgkmcnt(5)
	v_mfma_f32_32x32x16_bf16 v[82:97], v[100:103], v[120:123], v[82:97]
	v_add_f32_e32 v203, v181, v203
	v_add_f32_e32 v203, v215, v203
	v_add_f32_e32 v203, v216, v203
	v_add_f32_e32 v203, v180, v203
	s_waitcnt lgkmcnt(4)
	v_mfma_f32_32x32x16_bf16 v[66:81], v[136:139], v[120:123], v[66:81]
	v_mov_b32_e32 v204, v203
	v_cvt_pk_bf16_f32 v148, v148, v163
	v_cvt_pk_bf16_f32 v149, v149, v162
	v_cvt_pk_bf16_f32 v150, v150, v161
	ds_read_b128 v[100:103], v194 offset:32896
	ds_read_b128 v[136:139], v194 offset:41088
	s_waitcnt lgkmcnt(5)
	v_mfma_f32_32x32x16_bf16 v[82:97], v[172:175], v[116:119], v[82:97]
	v_cvt_pk_bf16_f32 v151, v151, v160
	v_cvt_pk_bf16_f32 v152, v152, v159
	v_cvt_pk_bf16_f32 v153, v153, v158
	v_cvt_pk_bf16_f32 v154, v154, v157
	s_waitcnt lgkmcnt(4)
	v_mfma_f32_32x32x16_bf16 v[66:81], v[228:231], v[116:119], v[66:81]
	v_cvt_pk_bf16_f32 v155, v155, v156
	v_cvt_pk_bf16_f32 v156, v217, v218
	v_cvt_pk_bf16_f32 v157, v219, v222
	ds_read_b128 v[172:175], v195 offset:32896
	ds_read_b128 v[228:231], v195 offset:41088
	s_waitcnt lgkmcnt(5)
	v_mfma_f32_32x32x16_bf16 v[82:97], v[234:237], v[112:115], v[82:97]
	v_cvt_pk_bf16_f32 v158, v208, v198
	v_cvt_pk_bf16_f32 v159, v201, v209
	v_cvt_pk_bf16_f32 v160, v214, v205
	s_waitcnt lgkmcnt(4)
	v_mfma_f32_32x32x16_bf16 v[66:81], v[238:241], v[112:115], v[66:81]
	v_cvt_pk_bf16_f32 v161, v206, v207
	v_cvt_pk_bf16_f32 v162, v181, v215
	v_cvt_pk_bf16_f32 v163, v216, v180
	ds_read_b64_tr_b16 v[206:207], v185 offset:0x5000
	ds_read_b64_tr_b16 v[208:209], v185 offset:0x5800
	ds_read_b64_tr_b16 v[224:225], v185 offset:0x6000
	ds_read_b64_tr_b16 v[226:227], v185 offset:0x6800
	s_waitcnt lgkmcnt(7)
	v_mfma_f32_32x32x16_bf16 v[82:97], v[100:103], v[108:111], v[82:97]
	s_nop 1
	v_permlane32_swap_b32_e32 v203, v204
	v_permlane32_swap_b32_e32 v148, v150
	v_permlane32_swap_b32_e32 v149, v151
	s_waitcnt lgkmcnt(6)
	v_mfma_f32_32x32x16_bf16 v[66:81], v[136:139], v[108:111], v[66:81]
	v_permlane32_swap_b32_e32 v152, v154
	v_permlane32_swap_b32_e32 v153, v155
	v_permlane32_swap_b32_e32 v156, v158
	s_waitcnt lgkmcnt(5)
	v_mfma_f32_32x32x16_bf16 v[82:97], v[172:175], v[104:107], v[82:97]
	v_permlane32_swap_b32_e32 v157, v159
	v_permlane32_swap_b32_e32 v160, v162
	v_permlane32_swap_b32_e32 v161, v163
	s_waitcnt lgkmcnt(4)
	v_mfma_f32_32x32x16_bf16 v[66:81], v[228:231], v[104:107], v[66:81]
	ds_read_b64_tr_b16 v[172:173], v185 offset:0x4000
	ds_read_b64_tr_b16 v[174:175], v185 offset:0x4800
	ds_read_b64_tr_b16 v[228:229], v185 offset:0x7000
	ds_read_b64_tr_b16 v[230:231], v185 offset:0x7800
	s_cmp_lt_u32 s3, s2
	s_cselect_b64 s[22:23], -1, 0
	s_cmp_ge_u32 s3, s2
	s_sub_i32 m0, 0, s100
	s_max_i32 m0, m0, 0
	s_add_i32 m0, m0, s32
	s_add_i32 m0, m0, s32
	s_sub_i32 m0, m0, 0xc000
	s_nop 0
	global_load_lds_dwordx4 v[248:249], off
	s_add_i32 m0, m0, 896
	s_nop 0
	global_load_lds_dwordx4 v[248:249], off offset:128
	v_lshl_add_u64 v[248:249], v[248:249], 0, v[250:251]
	s_add_i32 m0, s3, 1
	s_cmp_ge_u32 m0, s2
	s_cbranch_scc1 .LBB0_97
	s_max_i32 m0, s100, 0
	s_add_i32 m0, m0, s32
	s_nop 0
	global_load_lds_dwordx4 v[244:245], off
	s_add_i32 m0, m0, 0x2000
	s_nop 0
	global_load_lds_dwordx4 v[246:247], off
	v_lshl_add_u64 v[244:245], v[244:245], 0, v[250:251]
	v_lshl_add_u64 v[246:247], v[246:247], 0, v[250:251]
